# accumulator zeroing per unit uses v_mov_b64 pairs instead of 128 v_mov_b32
# baseline (speedup 1.0000x reference)
;     __device__ bool next(int i, Unit& u) const { const int L = i * G + c; if (L >= 384) return false; u.pm = L; u.pn = L / 6; return true; }
;     ...
;         const bool has_next = S.next(ui + 1, nxt);
;         const char* nA = has_next ? (const char*)g.A + (size_t)nxt.pm * tsA : cA; const char* nB = has_next ? (const char*)g.Bt + (size_t)nxt.pn * tsB : cB;
;     ...
; #pragma unroll
;         for (int a = 0; a < 2; ++a)
; #pragma unroll
;             for (int b = 0; b < 2; ++b)
; #pragma unroll
;                 for (int m = 0; m < 4; ++m)
; #pragma unroll
;                     for (int n = 0; n < 2; ++n) acc[a][b][m][n] = (f32x4){0.f, 0.f, 0.f, 0.f};
.LBB0_146:
	s_ashr_i32 s23, s22, 31
	s_lshl_b64 s[24:25], s[22:23], 20
	s_add_u32 s24, s96, s24
	s_addc_u32 s25, s97, s25
	s_ashr_i32 s21, s20, 31
	s_lshl_b64 s[26:27], s[20:21], 20
	s_add_u32 s26, s12, s26
	s_addc_u32 s27, s13, s27
	v_mov_b32_e32 v127, 0
	s_and_b64 vcc, exec, s[6:7]
	v_lshl_add_u32 v210, s28, 8, v193
	s_cbranch_vccnz .LBB0_157
	s_and_b64 s[28:29], s[8:9], exec
	s_cselect_b32 s21, s25, s35
	s_cselect_b32 s23, s24, s34
	s_cselect_b32 s57, s27, s31
	s_cselect_b32 s58, s26, s30
	s_add_u32 s28, s34, 0x80080
	s_addc_u32 s29, s35, 0
	v_ashrrev_i32_e32 v211, 31, v210
	s_add_u32 s59, s30, 0x100
	v_mov_b32_e32 v0, 0
	v_lshl_add_u64 v[212:213], v[210:211], 2, s[74:75]
	s_addc_u32 s60, s31, 0
	s_mov_b32 s61, 0
	v_mov_b32_e32 v1, 0
	v_mov_b64_e32 v[2:3], 0
	v_mov_b64_e32 v[8:9], 0
	v_mov_b64_e32 v[10:11], 0
	v_mov_b64_e32 v[16:17], 0
	v_mov_b64_e32 v[18:19], 0
	v_mov_b64_e32 v[24:25], 0
	v_mov_b64_e32 v[26:27], 0
	v_mov_b64_e32 v[32:33], 0
	v_mov_b64_e32 v[34:35], 0
	v_mov_b64_e32 v[40:41], 0
	v_mov_b64_e32 v[42:43], 0
	v_mov_b64_e32 v[48:49], 0
	v_mov_b64_e32 v[50:51], 0
	v_mov_b64_e32 v[56:57], 0
	v_mov_b64_e32 v[58:59], 0
	v_mov_b64_e32 v[4:5], 0
	v_mov_b64_e32 v[6:7], 0
	v_mov_b64_e32 v[12:13], 0
	v_mov_b64_e32 v[14:15], 0
	v_mov_b64_e32 v[20:21], 0
	v_mov_b64_e32 v[22:23], 0
	v_mov_b64_e32 v[28:29], 0
	v_mov_b64_e32 v[30:31], 0
	v_mov_b64_e32 v[36:37], 0
	v_mov_b64_e32 v[38:39], 0
	v_mov_b64_e32 v[44:45], 0
	v_mov_b64_e32 v[46:47], 0
	v_mov_b64_e32 v[52:53], 0
	v_mov_b64_e32 v[54:55], 0
	v_mov_b64_e32 v[60:61], 0
	v_mov_b64_e32 v[62:63], 0
	v_mov_b64_e32 v[64:65], 0
	v_mov_b64_e32 v[66:67], 0
	v_mov_b64_e32 v[72:73], 0
	v_mov_b64_e32 v[74:75], 0
	v_mov_b64_e32 v[80:81], 0
	v_mov_b64_e32 v[82:83], 0
	v_mov_b64_e32 v[88:89], 0
	v_mov_b64_e32 v[90:91], 0
	v_mov_b64_e32 v[96:97], 0
	v_mov_b64_e32 v[98:99], 0
	v_mov_b64_e32 v[104:105], 0
	v_mov_b64_e32 v[106:107], 0
	v_mov_b64_e32 v[112:113], 0
	v_mov_b64_e32 v[114:115], 0
	v_mov_b64_e32 v[120:121], 0
	v_mov_b64_e32 v[122:123], 0
	v_mov_b64_e32 v[68:69], 0
	v_mov_b64_e32 v[70:71], 0
	v_mov_b64_e32 v[76:77], 0
	v_mov_b64_e32 v[78:79], 0
	v_mov_b64_e32 v[84:85], 0
	v_mov_b64_e32 v[86:87], 0
	v_mov_b64_e32 v[92:93], 0
	v_mov_b64_e32 v[94:95], 0
	v_mov_b64_e32 v[100:101], 0
	v_mov_b64_e32 v[102:103], 0
	v_mov_b64_e32 v[108:109], 0
	v_mov_b64_e32 v[110:111], 0
	v_mov_b64_e32 v[116:117], 0
	v_mov_b64_e32 v[118:119], 0
	v_mov_b64_e32 v[124:125], 0
	v_mov_b64_e32 v[126:127], 0
	s_branch .LBB0_149

;     __device__ bool next(int i, Unit& u) const { const int L = i * G + c; if (L >= 384) return false; u.pm = L; u.pn = L / 6; return true; }
;     ...
;         const bool has_next = S.next(ui + 1, nxt);
;         const char* nA = has_next ? (const char*)g.A + (size_t)nxt.pm * tsA : cA; const char* nB = has_next ? (const char*)g.Bt + (size_t)nxt.pn * tsB : cB;
;         for (int t = 0; t < nt; t += 2) {
;             const bool last = (t == nt - 2);
;             const char* a1 = cA + (size_t)(t + 1) * kstep;
;             const char* a2 = last ? nA : cA + (size_t)(t + 2) * kstep; const char* b2 = last ? nB : cB + (size_t)(t + 2) * kstep;
;     ...
; #pragma unroll
;         for (int a = 0; a < 2; ++a)
; #pragma unroll
;             for (int b = 0; b < 2; ++b)
; #pragma unroll
;                 for (int m = 0; m < 4; ++m)
; #pragma unroll
;                     for (int n = 0; n < 2; ++n) acc[a][b][m][n] = (f32x4){0.f, 0.f, 0.f, 0.f};
.LBB0_244:
	v_mov_b32_e32 v179, 0
	s_andn2_b64 vcc, exec, s[18:19]
	v_mov_b32_e32 v178, 0
	v_mov_b64_e32 v[184:185], 0
	v_mov_b64_e32 v[182:183], 0
	v_mov_b64_e32 v[180:181], 0
	v_mov_b64_e32 v[168:169], 0
	v_mov_b64_e32 v[166:167], 0
	v_mov_b64_e32 v[164:165], 0
	v_mov_b64_e32 v[162:163], 0
	v_mov_b64_e32 v[152:153], 0
	v_mov_b64_e32 v[150:151], 0
	v_mov_b64_e32 v[148:149], 0
	v_mov_b64_e32 v[146:147], 0
	v_mov_b64_e32 v[120:121], 0
	v_mov_b64_e32 v[118:119], 0
	v_mov_b64_e32 v[116:117], 0
	v_mov_b64_e32 v[114:115], 0
	v_mov_b64_e32 v[194:195], 0
	v_mov_b64_e32 v[190:191], 0
	v_mov_b64_e32 v[188:189], 0
	v_mov_b64_e32 v[186:187], 0
	v_mov_b64_e32 v[176:177], 0
	v_mov_b64_e32 v[174:175], 0
	v_mov_b64_e32 v[172:173], 0
	v_mov_b64_e32 v[170:171], 0
	v_mov_b64_e32 v[160:161], 0
	v_mov_b64_e32 v[158:159], 0
	v_mov_b64_e32 v[156:157], 0
	v_mov_b64_e32 v[154:155], 0
	v_mov_b64_e32 v[144:145], 0
	v_mov_b64_e32 v[126:127], 0
	v_mov_b64_e32 v[124:125], 0
	v_mov_b64_e32 v[122:123], 0
	v_mov_b64_e32 v[102:103], 0
	v_mov_b64_e32 v[100:101], 0
	v_mov_b64_e32 v[98:99], 0
	v_mov_b64_e32 v[96:97], 0
	v_mov_b64_e32 v[86:87], 0
	v_mov_b64_e32 v[84:85], 0
	v_mov_b64_e32 v[82:83], 0
	v_mov_b64_e32 v[80:81], 0
	v_mov_b64_e32 v[70:71], 0
	v_mov_b64_e32 v[68:69], 0
	v_mov_b64_e32 v[66:67], 0
	v_mov_b64_e32 v[64:65], 0
	v_mov_b64_e32 v[54:55], 0
	v_mov_b64_e32 v[52:53], 0
	v_mov_b64_e32 v[50:51], 0
	v_mov_b64_e32 v[48:49], 0
	v_mov_b64_e32 v[110:111], 0
	v_mov_b64_e32 v[108:109], 0
	v_mov_b64_e32 v[106:107], 0
	v_mov_b64_e32 v[104:105], 0
	v_mov_b64_e32 v[94:95], 0
	v_mov_b64_e32 v[92:93], 0
	v_mov_b64_e32 v[90:91], 0
	v_mov_b64_e32 v[88:89], 0
	v_mov_b64_e32 v[78:79], 0
	v_mov_b64_e32 v[76:77], 0
	v_mov_b64_e32 v[74:75], 0
	v_mov_b64_e32 v[72:73], 0
	v_mov_b64_e32 v[62:63], 0
	v_mov_b64_e32 v[60:61], 0
	v_mov_b64_e32 v[58:59], 0
	v_mov_b64_e32 v[56:57], 0
	s_cbranch_vccnz .LBB0_248
	s_add_u32 s24, s24, 0x160080
	s_addc_u32 s25, s25, 0
	s_add_u32 s50, s26, 0x100
	v_mov_b32_e32 v0, 0
	s_addc_u32 s51, s27, 0
	s_mov_b32 s26, 0
	s_waitcnt lgkmcnt(0)
	v_mov_b32_e32 v1, 0
	v_mov_b64_e32 v[2:3], 0
	v_mov_b64_e32 v[4:5], 0
	v_mov_b64_e32 v[6:7], 0
	v_mov_b64_e32 v[8:9], 0
	v_mov_b64_e32 v[10:11], 0
	v_mov_b64_e32 v[12:13], 0
	v_mov_b64_e32 v[14:15], 0
	v_mov_b64_e32 v[20:21], 0
	v_mov_b64_e32 v[22:23], 0
	v_mov_b64_e32 v[28:29], 0
	v_mov_b64_e32 v[30:31], 0
	v_mov_b64_e32 v[36:37], 0
	v_mov_b64_e32 v[38:39], 0
	v_mov_b64_e32 v[44:45], 0
	v_mov_b64_e32 v[46:47], 0
	v_mov_b64_e32 v[16:17], 0
	v_mov_b64_e32 v[18:19], 0
	v_mov_b64_e32 v[24:25], 0
	v_mov_b64_e32 v[26:27], 0
	v_mov_b64_e32 v[32:33], 0
	v_mov_b64_e32 v[34:35], 0
	v_mov_b64_e32 v[40:41], 0
	v_mov_b64_e32 v[42:43], 0
	v_mov_b64_e32 v[48:49], 0
	v_mov_b64_e32 v[50:51], 0
	v_mov_b64_e32 v[52:53], 0
	v_mov_b64_e32 v[54:55], 0
	v_mov_b64_e32 v[56:57], 0
	v_mov_b64_e32 v[58:59], 0
	v_mov_b64_e32 v[60:61], 0
	v_mov_b64_e32 v[62:63], 0
	v_mov_b64_e32 v[64:65], 0
	v_mov_b64_e32 v[66:67], 0
	v_mov_b64_e32 v[68:69], 0
	v_mov_b64_e32 v[70:71], 0
	v_mov_b64_e32 v[72:73], 0
	v_mov_b64_e32 v[74:75], 0
	v_mov_b64_e32 v[76:77], 0
	v_mov_b64_e32 v[78:79], 0
	v_mov_b64_e32 v[84:85], 0
	v_mov_b64_e32 v[86:87], 0
	v_mov_b64_e32 v[92:93], 0
	v_mov_b64_e32 v[94:95], 0
	v_mov_b64_e32 v[100:101], 0
	v_mov_b64_e32 v[102:103], 0
	v_mov_b64_e32 v[108:109], 0
	v_mov_b64_e32 v[110:111], 0
	v_mov_b64_e32 v[80:81], 0
	v_mov_b64_e32 v[82:83], 0
	v_mov_b64_e32 v[88:89], 0
	v_mov_b64_e32 v[90:91], 0
	v_mov_b64_e32 v[96:97], 0
	v_mov_b64_e32 v[98:99], 0
	v_mov_b64_e32 v[104:105], 0
	v_mov_b64_e32 v[106:107], 0
	v_mov_b64_e32 v[112:113], 0
	v_mov_b64_e32 v[114:115], 0
	v_mov_b64_e32 v[116:117], 0
	v_mov_b64_e32 v[118:119], 0
	v_mov_b64_e32 v[120:121], 0
	v_mov_b64_e32 v[122:123], 0
	v_mov_b64_e32 v[124:125], 0
	v_mov_b64_e32 v[126:127], 0

;     __device__ bool next(int i, Unit& u) const { const int L = i * G + c; if (L >= 384) return false; u.pm = L; u.pn = L / 6; return true; }
;     ...
;         const bool has_next = S.next(ui + 1, nxt);
;         const char* nA = has_next ? (const char*)g.A + (size_t)nxt.pm * tsA : cA; const char* nB = has_next ? (const char*)g.Bt + (size_t)nxt.pn * tsB : cB;
;     ...
; #pragma unroll
;         for (int a = 0; a < 2; ++a)
; #pragma unroll
;             for (int b = 0; b < 2; ++b)
; #pragma unroll
;                 for (int m = 0; m < 4; ++m)
; #pragma unroll
;                     for (int n = 0; n < 2; ++n) acc[a][b][m][n] = (f32x4){0.f, 0.f, 0.f, 0.f};
.LBB0_368:
	s_ashr_i32 s23, s22, 31
	s_lshl_b64 s[24:25], s[22:23], 20
	s_add_u32 s24, s96, s24
	s_addc_u32 s25, s97, s25
	s_ashr_i32 s21, s20, 31
	s_lshl_b64 s[26:27], s[20:21], 20
	s_add_u32 s26, s3, s26
	s_addc_u32 s27, s4, s27
	s_andn2_b64 vcc, exec, s[14:15]
	v_mov_b32_e32 v127, 0
	s_cbranch_vccnz .LBB0_379
	s_and_b64 s[34:35], s[0:1], exec
	s_cselect_b32 s7, s25, s29
	s_cselect_b32 s21, s24, s28
	s_cselect_b32 s23, s27, s31
	s_cselect_b32 s68, s26, s30
	v_lshl_add_u32 v0, s6, 8, v205
	s_add_u32 s28, s28, 0x80080
	v_ashrrev_i32_e32 v1, 31, v0
	s_addc_u32 s29, s29, 0
	v_lshl_add_u64 v[224:225], v[0:1], 2, s[88:89]
	s_add_u32 s69, s30, 0x100
	v_mov_b32_e32 v0, 0
	s_addc_u32 s70, s31, 0
	s_mov_b32 s71, 0
	v_mov_b32_e32 v1, 0
	v_mov_b64_e32 v[2:3], 0
	v_mov_b64_e32 v[4:5], 0
	v_mov_b64_e32 v[6:7], 0
	v_mov_b64_e32 v[16:17], 0
	v_mov_b64_e32 v[18:19], 0
	v_mov_b64_e32 v[20:21], 0
	v_mov_b64_e32 v[22:23], 0
	v_mov_b64_e32 v[32:33], 0
	v_mov_b64_e32 v[34:35], 0
	v_mov_b64_e32 v[36:37], 0
	v_mov_b64_e32 v[38:39], 0
	v_mov_b64_e32 v[48:49], 0
	v_mov_b64_e32 v[50:51], 0
	v_mov_b64_e32 v[52:53], 0
	v_mov_b64_e32 v[54:55], 0
	v_mov_b64_e32 v[8:9], 0
	v_mov_b64_e32 v[10:11], 0
	v_mov_b64_e32 v[12:13], 0
	v_mov_b64_e32 v[14:15], 0
	v_mov_b64_e32 v[24:25], 0
	v_mov_b64_e32 v[26:27], 0
	v_mov_b64_e32 v[28:29], 0
	v_mov_b64_e32 v[30:31], 0
	v_mov_b64_e32 v[40:41], 0
	v_mov_b64_e32 v[42:43], 0
	v_mov_b64_e32 v[44:45], 0
	v_mov_b64_e32 v[46:47], 0
	v_mov_b64_e32 v[56:57], 0
	v_mov_b64_e32 v[58:59], 0
	v_mov_b64_e32 v[60:61], 0
	v_mov_b64_e32 v[62:63], 0
	v_mov_b64_e32 v[64:65], 0
	v_mov_b64_e32 v[66:67], 0
	v_mov_b64_e32 v[68:69], 0
	v_mov_b64_e32 v[70:71], 0
	v_mov_b64_e32 v[80:81], 0
	v_mov_b64_e32 v[82:83], 0
	v_mov_b64_e32 v[84:85], 0
	v_mov_b64_e32 v[86:87], 0
	v_mov_b64_e32 v[96:97], 0
	v_mov_b64_e32 v[98:99], 0
	v_mov_b64_e32 v[100:101], 0
	v_mov_b64_e32 v[102:103], 0
	v_mov_b64_e32 v[112:113], 0
	v_mov_b64_e32 v[114:115], 0
	v_mov_b64_e32 v[116:117], 0
	v_mov_b64_e32 v[118:119], 0
	v_mov_b64_e32 v[72:73], 0
	v_mov_b64_e32 v[74:75], 0
	v_mov_b64_e32 v[76:77], 0
	v_mov_b64_e32 v[78:79], 0
	v_mov_b64_e32 v[88:89], 0
	v_mov_b64_e32 v[90:91], 0
	v_mov_b64_e32 v[92:93], 0
	v_mov_b64_e32 v[94:95], 0
	v_mov_b64_e32 v[104:105], 0
	v_mov_b64_e32 v[106:107], 0
	v_mov_b64_e32 v[108:109], 0
	v_mov_b64_e32 v[110:111], 0
	v_mov_b64_e32 v[120:121], 0
	v_mov_b64_e32 v[122:123], 0
	v_mov_b64_e32 v[124:125], 0
	v_mov_b64_e32 v[126:127], 0
	s_branch .LBB0_371

;     ...
; #pragma unroll
;         for (int a = 0; a < 2; ++a)
; #pragma unroll
;             for (int b = 0; b < 2; ++b)
; #pragma unroll
;                 for (int m = 0; m < 4; ++m)
; #pragma unroll
;                     for (int n = 0; n < 2; ++n) acc[a][b][m][n] = (f32x4){0.f, 0.f, 0.f, 0.f};
.LBB0_646:
	s_add_i32 s34, s34, 1
	s_mul_i32 s16, s34, s33
	s_mov_b32 s19, s47
	s_add_i32 s47, s16, s2
	s_mul_hi_i32 s16, s47, 0x2aaaaaab
	s_lshr_b32 s17, s16, 31
	s_mov_b32 s18, s48
	s_add_i32 s48, s16, s17
	s_cmpk_lt_i32 s47, 0x180
	s_cselect_b64 s[20:21], -1, 0
	s_and_b64 s[16:17], s[20:21], exec
	s_cselect_b32 s16, s47, s19
	s_cselect_b32 s18, s48, s18
	s_ashr_i32 s17, s16, 31
	s_lshl_b64 s[16:17], s[16:17], 18
	s_add_u32 s16, s8, s16
	s_addc_u32 s17, s9, s17
	s_ashr_i32 s19, s18, 31
	s_lshl_b64 s[18:19], s[18:19], 17
	s_add_u32 s18, s4, s18
	v_mov_b32_e32 v127, 0
	s_addc_u32 s19, s5, s19
	s_and_b64 vcc, exec, s[0:1]
	v_mov_b32_e32 v126, 0
	v_mov_b64_e32 v[124:125], 0
	v_mov_b64_e32 v[122:123], 0
	v_mov_b64_e32 v[120:121], 0
	v_mov_b64_e32 v[110:111], 0
	v_mov_b64_e32 v[108:109], 0
	v_mov_b64_e32 v[106:107], 0
	v_mov_b64_e32 v[104:105], 0
	v_mov_b64_e32 v[94:95], 0
	v_mov_b64_e32 v[92:93], 0
	v_mov_b64_e32 v[90:91], 0
	v_mov_b64_e32 v[88:89], 0
	v_mov_b64_e32 v[78:79], 0
	v_mov_b64_e32 v[76:77], 0
	v_mov_b64_e32 v[74:75], 0
	v_mov_b64_e32 v[72:73], 0
	v_mov_b64_e32 v[118:119], 0
	v_mov_b64_e32 v[116:117], 0
	v_mov_b64_e32 v[114:115], 0
	v_mov_b64_e32 v[112:113], 0
	v_mov_b64_e32 v[102:103], 0
	v_mov_b64_e32 v[100:101], 0
	v_mov_b64_e32 v[98:99], 0
	v_mov_b64_e32 v[96:97], 0
	v_mov_b64_e32 v[86:87], 0
	v_mov_b64_e32 v[84:85], 0
	v_mov_b64_e32 v[82:83], 0
	v_mov_b64_e32 v[80:81], 0
	v_mov_b64_e32 v[70:71], 0
	v_mov_b64_e32 v[68:69], 0
	v_mov_b64_e32 v[66:67], 0
	v_mov_b64_e32 v[64:65], 0
	v_mov_b64_e32 v[62:63], 0
	v_mov_b64_e32 v[60:61], 0
	v_mov_b64_e32 v[58:59], 0
	v_mov_b64_e32 v[56:57], 0
	v_mov_b64_e32 v[46:47], 0
	v_mov_b64_e32 v[44:45], 0
	v_mov_b64_e32 v[42:43], 0
	v_mov_b64_e32 v[40:41], 0
	v_mov_b64_e32 v[30:31], 0
	v_mov_b64_e32 v[28:29], 0
	v_mov_b64_e32 v[26:27], 0
	v_mov_b64_e32 v[24:25], 0
	v_mov_b64_e32 v[14:15], 0
	v_mov_b64_e32 v[12:13], 0
	v_mov_b64_e32 v[10:11], 0
	v_mov_b64_e32 v[8:9], 0
	v_mov_b64_e32 v[54:55], 0
	v_mov_b64_e32 v[52:53], 0
	v_mov_b64_e32 v[50:51], 0
	v_mov_b64_e32 v[48:49], 0
	v_mov_b64_e32 v[38:39], 0
	v_mov_b64_e32 v[36:37], 0
	v_mov_b64_e32 v[34:35], 0
	v_mov_b64_e32 v[32:33], 0
	v_mov_b64_e32 v[22:23], 0
	v_mov_b64_e32 v[20:21], 0
	v_mov_b64_e32 v[18:19], 0
	v_mov_b64_e32 v[16:17], 0
	v_mov_b64_e32 v[6:7], 0
	v_mov_b64_e32 v[4:5], 0
	v_mov_b64_e32 v[2:3], 0
	v_mov_b64_e32 v[0:1], 0
	s_cbranch_vccnz .LBB0_649
	s_and_b64 s[26:27], s[20:21], exec
	s_cselect_b32 s50, s17, s23
	s_cselect_b32 s51, s16, s22
	s_cselect_b32 s52, s19, s25
	s_cselect_b32 s53, s18, s24
	s_add_u32 s22, s22, 0x20080
	s_addc_u32 s23, s23, 0
	s_add_u32 s54, s24, 0x100
	v_mov_b32_e32 v0, 0
	s_addc_u32 s55, s25, 0
	s_mov_b32 s24, 0
	v_mov_b32_e32 v1, 0
	v_mov_b64_e32 v[2:3], 0
	v_mov_b64_e32 v[4:5], 0
	v_mov_b64_e32 v[6:7], 0
	v_mov_b64_e32 v[16:17], 0
	v_mov_b64_e32 v[18:19], 0
	v_mov_b64_e32 v[20:21], 0
	v_mov_b64_e32 v[22:23], 0
	v_mov_b64_e32 v[32:33], 0
	v_mov_b64_e32 v[34:35], 0
	v_mov_b64_e32 v[36:37], 0
	v_mov_b64_e32 v[38:39], 0
	v_mov_b64_e32 v[48:49], 0
	v_mov_b64_e32 v[50:51], 0
	v_mov_b64_e32 v[52:53], 0
	v_mov_b64_e32 v[54:55], 0
	v_mov_b64_e32 v[8:9], 0
	v_mov_b64_e32 v[10:11], 0
	v_mov_b64_e32 v[12:13], 0
	v_mov_b64_e32 v[14:15], 0
	v_mov_b64_e32 v[24:25], 0
	v_mov_b64_e32 v[26:27], 0
	v_mov_b64_e32 v[28:29], 0
	v_mov_b64_e32 v[30:31], 0
	v_mov_b64_e32 v[40:41], 0
	v_mov_b64_e32 v[42:43], 0
	v_mov_b64_e32 v[44:45], 0
	v_mov_b64_e32 v[46:47], 0
	v_mov_b64_e32 v[56:57], 0
	v_mov_b64_e32 v[58:59], 0
	v_mov_b64_e32 v[60:61], 0
	v_mov_b64_e32 v[62:63], 0
	v_mov_b64_e32 v[64:65], 0
	v_mov_b64_e32 v[66:67], 0
	v_mov_b64_e32 v[68:69], 0
	v_mov_b64_e32 v[70:71], 0
	v_mov_b64_e32 v[80:81], 0
	v_mov_b64_e32 v[82:83], 0
	v_mov_b64_e32 v[84:85], 0
	v_mov_b64_e32 v[86:87], 0
	v_mov_b64_e32 v[96:97], 0
	v_mov_b64_e32 v[98:99], 0
	v_mov_b64_e32 v[100:101], 0
	v_mov_b64_e32 v[102:103], 0
	v_mov_b64_e32 v[112:113], 0
	v_mov_b64_e32 v[114:115], 0
	v_mov_b64_e32 v[116:117], 0
	v_mov_b64_e32 v[118:119], 0
	v_mov_b64_e32 v[72:73], 0
	v_mov_b64_e32 v[74:75], 0
	v_mov_b64_e32 v[76:77], 0
	v_mov_b64_e32 v[78:79], 0
	v_mov_b64_e32 v[88:89], 0
	v_mov_b64_e32 v[90:91], 0
	v_mov_b64_e32 v[92:93], 0
	v_mov_b64_e32 v[94:95], 0
	v_mov_b64_e32 v[104:105], 0
	v_mov_b64_e32 v[106:107], 0
	v_mov_b64_e32 v[108:109], 0
	v_mov_b64_e32 v[110:111], 0
	v_mov_b64_e32 v[120:121], 0
	v_mov_b64_e32 v[122:123], 0
	v_mov_b64_e32 v[124:125], 0
	v_mov_b64_e32 v[126:127], 0

;     ...
; #pragma unroll
;         for (int a = 0; a < 2; ++a)
; #pragma unroll
;             for (int b = 0; b < 2; ++b)
; #pragma unroll
;                 for (int m = 0; m < 4; ++m)
; #pragma unroll
;                     for (int n = 0; n < 2; ++n) acc[a][b][m][n] = (f32x4){0.f, 0.f, 0.f, 0.f};
.LBB0_885:
	s_add_i32 s38, s38, 1
	s_mul_i32 s16, s38, s33
	s_mov_b32 s19, s45
	s_add_i32 s45, s16, s2
	s_mul_hi_i32 s16, s45, 0x2aaaaaab
	s_lshr_b32 s17, s16, 31
	s_mov_b32 s18, s46
	s_add_i32 s46, s16, s17
	s_cmpk_lt_i32 s45, 0x180
	s_cselect_b64 s[20:21], -1, 0
	s_and_b64 s[16:17], s[20:21], exec
	s_cselect_b32 s16, s45, s19
	s_cselect_b32 s18, s46, s18
	s_ashr_i32 s17, s16, 31
	s_lshl_b64 s[16:17], s[16:17], 18
	s_add_u32 s16, s4, s16
	s_addc_u32 s17, s5, s17
	s_ashr_i32 s19, s18, 31
	s_lshl_b64 s[18:19], s[18:19], 18
	s_add_u32 s18, s30, s18
	v_mov_b32_e32 v127, 0
	s_addc_u32 s19, s31, s19
	s_and_b64 vcc, exec, s[0:1]
	v_mov_b32_e32 v126, 0
	v_mov_b64_e32 v[124:125], 0
	v_mov_b64_e32 v[122:123], 0
	v_mov_b64_e32 v[120:121], 0
	v_mov_b64_e32 v[110:111], 0
	v_mov_b64_e32 v[108:109], 0
	v_mov_b64_e32 v[106:107], 0
	v_mov_b64_e32 v[104:105], 0
	v_mov_b64_e32 v[94:95], 0
	v_mov_b64_e32 v[92:93], 0
	v_mov_b64_e32 v[90:91], 0
	v_mov_b64_e32 v[88:89], 0
	v_mov_b64_e32 v[78:79], 0
	v_mov_b64_e32 v[76:77], 0
	v_mov_b64_e32 v[74:75], 0
	v_mov_b64_e32 v[72:73], 0
	v_mov_b64_e32 v[118:119], 0
	v_mov_b64_e32 v[116:117], 0
	v_mov_b64_e32 v[114:115], 0
	v_mov_b64_e32 v[112:113], 0
	v_mov_b64_e32 v[102:103], 0
	v_mov_b64_e32 v[100:101], 0
	v_mov_b64_e32 v[98:99], 0
	v_mov_b64_e32 v[96:97], 0
	v_mov_b64_e32 v[86:87], 0
	v_mov_b64_e32 v[84:85], 0
	v_mov_b64_e32 v[82:83], 0
	v_mov_b64_e32 v[80:81], 0
	v_mov_b64_e32 v[70:71], 0
	v_mov_b64_e32 v[68:69], 0
	v_mov_b64_e32 v[66:67], 0
	v_mov_b64_e32 v[64:65], 0
	v_mov_b64_e32 v[62:63], 0
	v_mov_b64_e32 v[60:61], 0
	v_mov_b64_e32 v[58:59], 0
	v_mov_b64_e32 v[56:57], 0
	v_mov_b64_e32 v[46:47], 0
	v_mov_b64_e32 v[44:45], 0
	v_mov_b64_e32 v[42:43], 0
	v_mov_b64_e32 v[40:41], 0
	v_mov_b64_e32 v[30:31], 0
	v_mov_b64_e32 v[28:29], 0
	v_mov_b64_e32 v[26:27], 0
	v_mov_b64_e32 v[24:25], 0
	v_mov_b64_e32 v[14:15], 0
	v_mov_b64_e32 v[12:13], 0
	v_mov_b64_e32 v[10:11], 0
	v_mov_b64_e32 v[8:9], 0
	v_mov_b64_e32 v[54:55], 0
	v_mov_b64_e32 v[52:53], 0
	v_mov_b64_e32 v[50:51], 0
	v_mov_b64_e32 v[48:49], 0
	v_mov_b64_e32 v[38:39], 0
	v_mov_b64_e32 v[36:37], 0
	v_mov_b64_e32 v[34:35], 0
	v_mov_b64_e32 v[32:33], 0
	v_mov_b64_e32 v[22:23], 0
	v_mov_b64_e32 v[20:21], 0
	v_mov_b64_e32 v[18:19], 0
	v_mov_b64_e32 v[16:17], 0
	v_mov_b64_e32 v[6:7], 0
	v_mov_b64_e32 v[4:5], 0
	v_mov_b64_e32 v[2:3], 0
	v_mov_b64_e32 v[0:1], 0
	s_cbranch_vccnz .LBB0_888
	s_and_b64 s[28:29], s[20:21], exec
	s_cselect_b32 s23, s17, s25
	s_cselect_b32 s48, s16, s24
	s_cselect_b32 s49, s19, s27
	s_cselect_b32 s50, s18, s26
	s_add_u32 s24, s24, 0x20080
	s_addc_u32 s25, s25, 0
	s_add_u32 s51, s26, 0x100
	v_mov_b32_e32 v0, 0
	s_addc_u32 s52, s27, 0
	s_mov_b32 s26, 0
	v_mov_b32_e32 v1, 0
	v_mov_b64_e32 v[2:3], 0
	v_mov_b64_e32 v[4:5], 0
	v_mov_b64_e32 v[6:7], 0
	v_mov_b64_e32 v[16:17], 0
	v_mov_b64_e32 v[18:19], 0
	v_mov_b64_e32 v[20:21], 0
	v_mov_b64_e32 v[22:23], 0
	v_mov_b64_e32 v[32:33], 0
	v_mov_b64_e32 v[34:35], 0
	v_mov_b64_e32 v[36:37], 0
	v_mov_b64_e32 v[38:39], 0
	v_mov_b64_e32 v[48:49], 0
	v_mov_b64_e32 v[50:51], 0
	v_mov_b64_e32 v[52:53], 0
	v_mov_b64_e32 v[54:55], 0
	v_mov_b64_e32 v[8:9], 0
	v_mov_b64_e32 v[10:11], 0
	v_mov_b64_e32 v[12:13], 0
	v_mov_b64_e32 v[14:15], 0
	v_mov_b64_e32 v[24:25], 0
	v_mov_b64_e32 v[26:27], 0
	v_mov_b64_e32 v[28:29], 0
	v_mov_b64_e32 v[30:31], 0
	v_mov_b64_e32 v[40:41], 0
	v_mov_b64_e32 v[42:43], 0
	v_mov_b64_e32 v[44:45], 0
	v_mov_b64_e32 v[46:47], 0
	v_mov_b64_e32 v[56:57], 0
	v_mov_b64_e32 v[58:59], 0
	v_mov_b64_e32 v[60:61], 0
	v_mov_b64_e32 v[62:63], 0
	v_mov_b64_e32 v[64:65], 0
	v_mov_b64_e32 v[66:67], 0
	v_mov_b64_e32 v[68:69], 0
	v_mov_b64_e32 v[70:71], 0
	v_mov_b64_e32 v[80:81], 0
	v_mov_b64_e32 v[82:83], 0
	v_mov_b64_e32 v[84:85], 0
	v_mov_b64_e32 v[86:87], 0
	v_mov_b64_e32 v[96:97], 0
	v_mov_b64_e32 v[98:99], 0
	v_mov_b64_e32 v[100:101], 0
	v_mov_b64_e32 v[102:103], 0
	v_mov_b64_e32 v[112:113], 0
	v_mov_b64_e32 v[114:115], 0
	v_mov_b64_e32 v[116:117], 0
	v_mov_b64_e32 v[118:119], 0
	v_mov_b64_e32 v[72:73], 0
	v_mov_b64_e32 v[74:75], 0
	v_mov_b64_e32 v[76:77], 0
	v_mov_b64_e32 v[78:79], 0
	v_mov_b64_e32 v[88:89], 0
	v_mov_b64_e32 v[90:91], 0
	v_mov_b64_e32 v[92:93], 0
	v_mov_b64_e32 v[94:95], 0
	v_mov_b64_e32 v[104:105], 0
	v_mov_b64_e32 v[106:107], 0
	v_mov_b64_e32 v[108:109], 0
	v_mov_b64_e32 v[110:111], 0
	v_mov_b64_e32 v[120:121], 0
	v_mov_b64_e32 v[122:123], 0
	v_mov_b64_e32 v[124:125], 0
	v_mov_b64_e32 v[126:127], 0

;     __device__ bool next(int i, Unit& u) const { const int L = i * G + c; if (L >= 384) return false; u.pm = L; u.pn = L / 6; return true; }
;     ...
;         const bool has_next = S.next(ui + 1, nxt);
;         const char* nA = has_next ? (const char*)g.A + (size_t)nxt.pm * tsA : cA; const char* nB = has_next ? (const char*)g.Bt + (size_t)nxt.pn * tsB : cB;
;     ...
; #pragma unroll
;         for (int a = 0; a < 2; ++a)
; #pragma unroll
;             for (int b = 0; b < 2; ++b)
; #pragma unroll
;                 for (int m = 0; m < 4; ++m)
; #pragma unroll
;                     for (int n = 0; n < 2; ++n) acc[a][b][m][n] = (f32x4){0.f, 0.f, 0.f, 0.f};
.LBB0_957:
	s_ashr_i32 s21, s20, 31
	s_lshl_b64 s[22:23], s[20:21], 19
	s_add_u32 s22, s8, s22
	s_addc_u32 s23, s9, s23
	s_ashr_i32 s19, s18, 31
	s_lshl_b64 s[24:25], s[18:19], 19
	s_add_u32 s24, s6, s24
	v_mov_b32_e32 v139, 0
	s_addc_u32 s25, s7, s25
	s_andn2_b64 vcc, exec, s[14:15]
	v_mov_b32_e32 v138, v139
	v_mov_b32_e32 v137, v139
	v_mov_b32_e32 v136, v139
	v_mov_b32_e32 v143, v139
	v_mov_b32_e32 v142, v139
	v_mov_b32_e32 v141, v139
	v_mov_b32_e32 v140, v139
	v_mov_b32_e32 v127, v139
	v_mov_b32_e32 v126, v139
	v_mov_b32_e32 v125, v139
	v_mov_b32_e32 v124, v139
	v_mov_b32_e32 v123, v139
	v_mov_b32_e32 v122, v139
	v_mov_b32_e32 v121, v139
	v_mov_b32_e32 v120, v139
	v_mov_b32_e32 v103, v139
	v_mov_b32_e32 v102, v139
	v_mov_b32_e32 v101, v139
	v_mov_b32_e32 v100, v139
	v_mov_b32_e32 v99, v139
	v_mov_b32_e32 v98, v139
	v_mov_b32_e32 v97, v139
	v_mov_b32_e32 v96, v139
	v_mov_b32_e32 v79, v139
	v_mov_b32_e32 v78, v139
	v_mov_b32_e32 v77, v139
	v_mov_b32_e32 v76, v139
	v_mov_b32_e32 v75, v139
	v_mov_b32_e32 v74, v139
	v_mov_b32_e32 v73, v139
	v_mov_b32_e32 v72, v139
	v_mov_b32_e32 v135, v139
	v_mov_b32_e32 v134, v139
	v_mov_b32_e32 v133, v139
	v_mov_b32_e32 v132, v139
	v_mov_b32_e32 v131, v139
	v_mov_b32_e32 v130, v139
	v_mov_b32_e32 v129, v139
	v_mov_b32_e32 v128, v139
	v_mov_b32_e32 v119, v139
	v_mov_b32_e32 v118, v139
	v_mov_b32_e32 v117, v139
	v_mov_b32_e32 v116, v139
	v_mov_b32_e32 v115, v139
	v_mov_b32_e32 v114, v139
	v_mov_b32_e32 v113, v139
	v_mov_b32_e32 v112, v139
	v_mov_b32_e32 v87, v139
	v_mov_b32_e32 v86, v139
	v_mov_b32_e32 v85, v139
	v_mov_b32_e32 v84, v139
	v_mov_b32_e32 v83, v139
	v_mov_b32_e32 v82, v139
	v_mov_b32_e32 v81, v139
	v_mov_b32_e32 v80, v139
	v_mov_b32_e32 v71, v139
	v_mov_b32_e32 v70, v139
	v_mov_b32_e32 v69, v139
	v_mov_b32_e32 v68, v139
	v_mov_b32_e32 v67, v139
	v_mov_b32_e32 v66, v139
	v_mov_b32_e32 v65, v139
	v_mov_b32_e32 v64, v139
	v_mov_b32_e32 v63, v139
	v_mov_b32_e32 v62, v139
	v_mov_b32_e32 v61, v139
	v_mov_b32_e32 v60, v139
	v_mov_b32_e32 v59, v139
	v_mov_b32_e32 v58, v139
	v_mov_b32_e32 v57, v139
	v_mov_b32_e32 v56, v139
	v_mov_b32_e32 v47, v139
	v_mov_b32_e32 v46, v139
	v_mov_b32_e32 v45, v139
	v_mov_b32_e32 v44, v139
	v_mov_b32_e32 v43, v139
	v_mov_b32_e32 v42, v139
	v_mov_b32_e32 v41, v139
	v_mov_b32_e32 v40, v139
	v_mov_b32_e32 v31, v139
	v_mov_b32_e32 v30, v139
	v_mov_b32_e32 v29, v139
	v_mov_b32_e32 v28, v139
	v_mov_b32_e32 v27, v139
	v_mov_b32_e32 v26, v139
	v_mov_b32_e32 v25, v139
	v_mov_b32_e32 v24, v139
	v_mov_b32_e32 v15, v139
	v_mov_b32_e32 v14, v139
	v_mov_b32_e32 v13, v139
	v_mov_b32_e32 v12, v139
	v_mov_b32_e32 v11, v139
	v_mov_b32_e32 v10, v139
	v_mov_b32_e32 v9, v139
	v_mov_b32_e32 v8, v139
	v_mov_b32_e32 v55, v139
	v_mov_b32_e32 v54, v139
	v_mov_b32_e32 v53, v139
	v_mov_b32_e32 v52, v139
	v_mov_b32_e32 v51, v139
	v_mov_b32_e32 v50, v139
	v_mov_b32_e32 v49, v139
	v_mov_b32_e32 v48, v139
	v_mov_b32_e32 v39, v139
	v_mov_b32_e32 v38, v139
	v_mov_b32_e32 v37, v139
	v_mov_b32_e32 v36, v139
	v_mov_b32_e32 v35, v139
	v_mov_b32_e32 v34, v139
	v_mov_b32_e32 v33, v139
	v_mov_b32_e32 v32, v139
	v_mov_b32_e32 v23, v139
	v_mov_b32_e32 v22, v139
	v_mov_b32_e32 v21, v139
	v_mov_b32_e32 v20, v139
	v_mov_b32_e32 v19, v139
	v_mov_b32_e32 v18, v139
	v_mov_b32_e32 v17, v139
	v_mov_b32_e32 v16, v139
	v_mov_b32_e32 v7, v139
	v_mov_b32_e32 v6, v139
	v_mov_b32_e32 v5, v139
	v_mov_b32_e32 v4, v139
	v_mov_b32_e32 v3, v139
	v_mov_b32_e32 v2, v139
	v_mov_b32_e32 v1, v139
	v_mov_b32_e32 v0, v139
	s_cbranch_vccnz .LBB0_960
	s_and_b64 s[34:35], s[0:1], exec
	s_cselect_b32 s19, s23, s29
	s_cselect_b32 s21, s22, s28
	s_cselect_b32 s47, s25, s31
	s_cselect_b32 s48, s24, s30
	s_add_u32 s28, s28, 0x40080
	s_addc_u32 s29, s29, 0
	s_add_u32 s49, s30, 0x100
	v_mov_b32_e32 v0, 0
	s_addc_u32 s50, s31, 0
	s_mov_b32 s30, 0
	v_mov_b32_e32 v1, 0
	v_mov_b64_e32 v[2:3], 0
	v_mov_b64_e32 v[4:5], 0
	v_mov_b64_e32 v[6:7], 0
	v_mov_b64_e32 v[16:17], 0
	v_mov_b64_e32 v[18:19], 0
	v_mov_b64_e32 v[20:21], 0
	v_mov_b64_e32 v[22:23], 0
	v_mov_b64_e32 v[32:33], 0
	v_mov_b64_e32 v[34:35], 0
	v_mov_b64_e32 v[36:37], 0
	v_mov_b64_e32 v[38:39], 0
	v_mov_b64_e32 v[48:49], 0
	v_mov_b64_e32 v[50:51], 0
	v_mov_b64_e32 v[52:53], 0
	v_mov_b64_e32 v[54:55], 0
	v_mov_b64_e32 v[8:9], 0
	v_mov_b64_e32 v[10:11], 0
	v_mov_b64_e32 v[12:13], 0
	v_mov_b64_e32 v[14:15], 0
	v_mov_b64_e32 v[24:25], 0
	v_mov_b64_e32 v[26:27], 0
	v_mov_b64_e32 v[28:29], 0
	v_mov_b64_e32 v[30:31], 0
	v_mov_b64_e32 v[40:41], 0
	v_mov_b64_e32 v[42:43], 0
	v_mov_b64_e32 v[44:45], 0
	v_mov_b64_e32 v[46:47], 0
	v_mov_b64_e32 v[56:57], 0
	v_mov_b64_e32 v[58:59], 0
	v_mov_b64_e32 v[60:61], 0
	v_mov_b64_e32 v[62:63], 0
	v_mov_b64_e32 v[64:65], 0
	v_mov_b64_e32 v[66:67], 0
	v_mov_b64_e32 v[68:69], 0
	v_mov_b64_e32 v[70:71], 0
	v_mov_b64_e32 v[80:81], 0
	v_mov_b64_e32 v[82:83], 0
	v_mov_b64_e32 v[84:85], 0
	v_mov_b64_e32 v[86:87], 0
	v_mov_b64_e32 v[112:113], 0
	v_mov_b64_e32 v[114:115], 0
	v_mov_b64_e32 v[116:117], 0
	v_mov_b64_e32 v[118:119], 0
	v_mov_b64_e32 v[128:129], 0
	v_mov_b64_e32 v[130:131], 0
	v_mov_b64_e32 v[132:133], 0
	v_mov_b64_e32 v[134:135], 0
	v_mov_b64_e32 v[72:73], 0
	v_mov_b64_e32 v[74:75], 0
	v_mov_b64_e32 v[76:77], 0
	v_mov_b64_e32 v[78:79], 0
	v_mov_b64_e32 v[96:97], 0
	v_mov_b64_e32 v[98:99], 0
	v_mov_b64_e32 v[100:101], 0
	v_mov_b64_e32 v[102:103], 0
	v_mov_b64_e32 v[120:121], 0
	v_mov_b64_e32 v[122:123], 0
	v_mov_b64_e32 v[124:125], 0
	v_mov_b64_e32 v[126:127], 0
	v_mov_b64_e32 v[140:141], 0
	v_mov_b64_e32 v[142:143], 0
	v_mov_b64_e32 v[136:137], 0
	v_mov_b64_e32 v[138:139], 0

;     __device__ bool next(int i, Unit& u) const { const int L = i * G + c; if (L >= 384) return false; u.pm = L; u.pn = L / 6; return true; }
;     ...
;         const bool has_next = S.next(ui + 1, nxt);
;         const char* nA = has_next ? (const char*)g.A + (size_t)nxt.pm * tsA : cA; const char* nB = has_next ? (const char*)g.Bt + (size_t)nxt.pn * tsB : cB;
;     ...
; #pragma unroll
;         for (int a = 0; a < 2; ++a)
; #pragma unroll
;             for (int b = 0; b < 2; ++b)
; #pragma unroll
;                 for (int m = 0; m < 4; ++m)
; #pragma unroll
;                     for (int n = 0; n < 2; ++n) acc[a][b][m][n] = (f32x4){0.f, 0.f, 0.f, 0.f};
.LBB0_1038:
	s_ashr_i32 s23, s22, 31
	s_lshl_b64 s[24:25], s[22:23], 19
	s_add_u32 s24, s3, s24
	s_addc_u32 s25, s4, s25
	s_ashr_i32 s21, s20, 31
	s_lshl_b64 s[26:27], s[20:21], 19
	s_add_u32 s26, s5, s26
	v_mov_b32_e32 v127, 0
	s_addc_u32 s27, s36, s27
	s_and_b64 vcc, exec, s[0:1]
	v_mov_b32_e32 v126, 0
	v_mov_b64_e32 v[124:125], 0
	v_mov_b64_e32 v[122:123], 0
	v_mov_b64_e32 v[120:121], 0
	v_mov_b64_e32 v[110:111], 0
	v_mov_b64_e32 v[108:109], 0
	v_mov_b64_e32 v[106:107], 0
	v_mov_b64_e32 v[104:105], 0
	v_mov_b64_e32 v[94:95], 0
	v_mov_b64_e32 v[92:93], 0
	v_mov_b64_e32 v[90:91], 0
	v_mov_b64_e32 v[88:89], 0
	v_mov_b64_e32 v[78:79], 0
	v_mov_b64_e32 v[76:77], 0
	v_mov_b64_e32 v[74:75], 0
	v_mov_b64_e32 v[72:73], 0
	v_mov_b64_e32 v[118:119], 0
	v_mov_b64_e32 v[116:117], 0
	v_mov_b64_e32 v[114:115], 0
	v_mov_b64_e32 v[112:113], 0
	v_mov_b64_e32 v[102:103], 0
	v_mov_b64_e32 v[100:101], 0
	v_mov_b64_e32 v[98:99], 0
	v_mov_b64_e32 v[96:97], 0
	v_mov_b64_e32 v[86:87], 0
	v_mov_b64_e32 v[84:85], 0
	v_mov_b64_e32 v[82:83], 0
	v_mov_b64_e32 v[80:81], 0
	v_mov_b64_e32 v[70:71], 0
	v_mov_b64_e32 v[68:69], 0
	v_mov_b64_e32 v[66:67], 0
	v_mov_b64_e32 v[64:65], 0
	v_mov_b64_e32 v[62:63], 0
	v_mov_b64_e32 v[60:61], 0
	v_mov_b64_e32 v[58:59], 0
	v_mov_b64_e32 v[56:57], 0
	v_mov_b64_e32 v[46:47], 0
	v_mov_b64_e32 v[44:45], 0
	v_mov_b64_e32 v[42:43], 0
	v_mov_b64_e32 v[40:41], 0
	v_mov_b64_e32 v[30:31], 0
	v_mov_b64_e32 v[28:29], 0
	v_mov_b64_e32 v[26:27], 0
	v_mov_b64_e32 v[24:25], 0
	v_mov_b64_e32 v[14:15], 0
	v_mov_b64_e32 v[12:13], 0
	v_mov_b64_e32 v[10:11], 0
	v_mov_b64_e32 v[8:9], 0
	v_mov_b64_e32 v[54:55], 0
	v_mov_b64_e32 v[52:53], 0
	v_mov_b64_e32 v[50:51], 0
	v_mov_b64_e32 v[48:49], 0
	v_mov_b64_e32 v[38:39], 0
	v_mov_b64_e32 v[36:37], 0
	v_mov_b64_e32 v[34:35], 0
	v_mov_b64_e32 v[32:33], 0
	v_mov_b64_e32 v[22:23], 0
	v_mov_b64_e32 v[20:21], 0
	v_mov_b64_e32 v[18:19], 0
	v_mov_b64_e32 v[16:17], 0
	v_mov_b64_e32 v[6:7], 0
	v_mov_b64_e32 v[4:5], 0
	v_mov_b64_e32 v[2:3], 0
	v_mov_b64_e32 v[0:1], 0
	s_cbranch_vccnz .LBB0_1041
	s_and_b64 s[34:35], s[6:7], exec
	s_cselect_b32 s21, s25, s29
	s_cselect_b32 s23, s24, s28
	s_cselect_b32 s52, s27, s31
	s_cselect_b32 s53, s26, s30
	s_add_u32 s28, s28, 0x40080
	s_addc_u32 s29, s29, 0
	s_add_u32 s54, s30, 0x100
	v_mov_b32_e32 v0, 0
	s_addc_u32 s55, s31, 0
	s_mov_b32 s30, 0
	v_mov_b32_e32 v1, 0
	v_mov_b64_e32 v[2:3], 0
	v_mov_b64_e32 v[4:5], 0
	v_mov_b64_e32 v[6:7], 0
	v_mov_b64_e32 v[16:17], 0
	v_mov_b64_e32 v[18:19], 0
	v_mov_b64_e32 v[20:21], 0
	v_mov_b64_e32 v[22:23], 0
	v_mov_b64_e32 v[32:33], 0
	v_mov_b64_e32 v[34:35], 0
	v_mov_b64_e32 v[36:37], 0
	v_mov_b64_e32 v[38:39], 0
	v_mov_b64_e32 v[48:49], 0
	v_mov_b64_e32 v[50:51], 0
	v_mov_b64_e32 v[52:53], 0
	v_mov_b64_e32 v[54:55], 0
	v_mov_b64_e32 v[8:9], 0
	v_mov_b64_e32 v[10:11], 0
	v_mov_b64_e32 v[12:13], 0
	v_mov_b64_e32 v[14:15], 0
	v_mov_b64_e32 v[24:25], 0
	v_mov_b64_e32 v[26:27], 0
	v_mov_b64_e32 v[28:29], 0
	v_mov_b64_e32 v[30:31], 0
	v_mov_b64_e32 v[40:41], 0
	v_mov_b64_e32 v[42:43], 0
	v_mov_b64_e32 v[44:45], 0
	v_mov_b64_e32 v[46:47], 0
	v_mov_b64_e32 v[56:57], 0
	v_mov_b64_e32 v[58:59], 0
	v_mov_b64_e32 v[60:61], 0
	v_mov_b64_e32 v[62:63], 0
	v_mov_b64_e32 v[64:65], 0
	v_mov_b64_e32 v[66:67], 0
	v_mov_b64_e32 v[68:69], 0
	v_mov_b64_e32 v[70:71], 0
	v_mov_b64_e32 v[80:81], 0
	v_mov_b64_e32 v[82:83], 0
	v_mov_b64_e32 v[84:85], 0
	v_mov_b64_e32 v[86:87], 0
	v_mov_b64_e32 v[96:97], 0
	v_mov_b64_e32 v[98:99], 0
	v_mov_b64_e32 v[100:101], 0
	v_mov_b64_e32 v[102:103], 0
	v_mov_b64_e32 v[112:113], 0
	v_mov_b64_e32 v[114:115], 0
	v_mov_b64_e32 v[116:117], 0
	v_mov_b64_e32 v[118:119], 0
	v_mov_b64_e32 v[72:73], 0
	v_mov_b64_e32 v[74:75], 0
	v_mov_b64_e32 v[76:77], 0
	v_mov_b64_e32 v[78:79], 0
	v_mov_b64_e32 v[88:89], 0
	v_mov_b64_e32 v[90:91], 0
	v_mov_b64_e32 v[92:93], 0
	v_mov_b64_e32 v[94:95], 0
	v_mov_b64_e32 v[104:105], 0
	v_mov_b64_e32 v[106:107], 0
	v_mov_b64_e32 v[108:109], 0
	v_mov_b64_e32 v[110:111], 0
	v_mov_b64_e32 v[120:121], 0
	v_mov_b64_e32 v[122:123], 0
	v_mov_b64_e32 v[124:125], 0
	v_mov_b64_e32 v[126:127], 0

;     __device__ bool next(int i, Unit& u) const { const int L = i * G + c; if (L >= 384) return false; u.pm = L; u.pn = L / 6; return true; }
;     ...
;         const bool has_next = S.next(ui + 1, nxt);
;         const char* nA = has_next ? (const char*)g.A + (size_t)nxt.pm * tsA : cA; const char* nB = has_next ? (const char*)g.Bt + (size_t)nxt.pn * tsB : cB;
;     ...
; #pragma unroll
;         for (int a = 0; a < 2; ++a)
; #pragma unroll
;             for (int b = 0; b < 2; ++b)
; #pragma unroll
;                 for (int m = 0; m < 4; ++m)
; #pragma unroll
;                     for (int n = 0; n < 2; ++n) acc[a][b][m][n] = (f32x4){0.f, 0.f, 0.f, 0.f};
.LBB0_1110:
	s_ashr_i32 s23, s22, 31
	s_lshl_b64 s[24:25], s[22:23], 19
	s_add_u32 s24, s94, s24
	s_addc_u32 s25, s95, s25
	s_ashr_i32 s21, s20, 31
	s_lshl_b64 s[26:27], s[20:21], 19
	s_add_u32 s26, s3, s26
	v_mov_b32_e32 v127, 0
	s_addc_u32 s27, s4, s27
	s_and_b64 vcc, exec, s[0:1]
	v_mov_b32_e32 v126, 0
	v_mov_b64_e32 v[124:125], 0
	v_mov_b64_e32 v[122:123], 0
	v_mov_b64_e32 v[120:121], 0
	v_mov_b64_e32 v[110:111], 0
	v_mov_b64_e32 v[108:109], 0
	v_mov_b64_e32 v[106:107], 0
	v_mov_b64_e32 v[104:105], 0
	v_mov_b64_e32 v[94:95], 0
	v_mov_b64_e32 v[92:93], 0
	v_mov_b64_e32 v[90:91], 0
	v_mov_b64_e32 v[88:89], 0
	v_mov_b64_e32 v[78:79], 0
	v_mov_b64_e32 v[76:77], 0
	v_mov_b64_e32 v[74:75], 0
	v_mov_b64_e32 v[72:73], 0
	v_mov_b64_e32 v[118:119], 0
	v_mov_b64_e32 v[116:117], 0
	v_mov_b64_e32 v[114:115], 0
	v_mov_b64_e32 v[112:113], 0
	v_mov_b64_e32 v[102:103], 0
	v_mov_b64_e32 v[100:101], 0
	v_mov_b64_e32 v[98:99], 0
	v_mov_b64_e32 v[96:97], 0
	v_mov_b64_e32 v[86:87], 0
	v_mov_b64_e32 v[84:85], 0
	v_mov_b64_e32 v[82:83], 0
	v_mov_b64_e32 v[80:81], 0
	v_mov_b64_e32 v[70:71], 0
	v_mov_b64_e32 v[68:69], 0
	v_mov_b64_e32 v[66:67], 0
	v_mov_b64_e32 v[64:65], 0
	v_mov_b64_e32 v[62:63], 0
	v_mov_b64_e32 v[60:61], 0
	v_mov_b64_e32 v[58:59], 0
	v_mov_b64_e32 v[56:57], 0
	v_mov_b64_e32 v[46:47], 0
	v_mov_b64_e32 v[44:45], 0
	v_mov_b64_e32 v[42:43], 0
	v_mov_b64_e32 v[40:41], 0
	v_mov_b64_e32 v[30:31], 0
	v_mov_b64_e32 v[28:29], 0
	v_mov_b64_e32 v[26:27], 0
	v_mov_b64_e32 v[24:25], 0
	v_mov_b64_e32 v[14:15], 0
	v_mov_b64_e32 v[12:13], 0
	v_mov_b64_e32 v[10:11], 0
	v_mov_b64_e32 v[8:9], 0
	v_mov_b64_e32 v[54:55], 0
	v_mov_b64_e32 v[52:53], 0
	v_mov_b64_e32 v[50:51], 0
	v_mov_b64_e32 v[48:49], 0
	v_mov_b64_e32 v[38:39], 0
	v_mov_b64_e32 v[36:37], 0
	v_mov_b64_e32 v[34:35], 0
	v_mov_b64_e32 v[32:33], 0
	v_mov_b64_e32 v[22:23], 0
	v_mov_b64_e32 v[20:21], 0
	v_mov_b64_e32 v[18:19], 0
	v_mov_b64_e32 v[16:17], 0
	v_mov_b64_e32 v[6:7], 0
	v_mov_b64_e32 v[4:5], 0
	v_mov_b64_e32 v[2:3], 0
	v_mov_b64_e32 v[0:1], 0
	s_cbranch_vccnz .LBB0_1113
	s_and_b64 s[34:35], s[6:7], exec
	s_cselect_b32 s21, s25, s29
	s_cselect_b32 s23, s24, s28
	s_cselect_b32 s50, s27, s31
	s_cselect_b32 s51, s26, s30
	s_add_u32 s28, s28, 0x40080
	s_addc_u32 s29, s29, 0
	s_add_u32 s52, s30, 0x100
	v_mov_b32_e32 v0, 0
	s_addc_u32 s53, s31, 0
	s_mov_b32 s30, 0
	v_mov_b32_e32 v1, 0
	v_mov_b64_e32 v[2:3], 0
	v_mov_b64_e32 v[4:5], 0
	v_mov_b64_e32 v[6:7], 0
	v_mov_b64_e32 v[16:17], 0
	v_mov_b64_e32 v[18:19], 0
	v_mov_b64_e32 v[20:21], 0
	v_mov_b64_e32 v[22:23], 0
	v_mov_b64_e32 v[32:33], 0
	v_mov_b64_e32 v[34:35], 0
	v_mov_b64_e32 v[36:37], 0
	v_mov_b64_e32 v[38:39], 0
	v_mov_b64_e32 v[48:49], 0
	v_mov_b64_e32 v[50:51], 0
	v_mov_b64_e32 v[52:53], 0
	v_mov_b64_e32 v[54:55], 0
	v_mov_b64_e32 v[8:9], 0
	v_mov_b64_e32 v[10:11], 0
	v_mov_b64_e32 v[12:13], 0
	v_mov_b64_e32 v[14:15], 0
	v_mov_b64_e32 v[24:25], 0
	v_mov_b64_e32 v[26:27], 0
	v_mov_b64_e32 v[28:29], 0
	v_mov_b64_e32 v[30:31], 0
	v_mov_b64_e32 v[40:41], 0
	v_mov_b64_e32 v[42:43], 0
	v_mov_b64_e32 v[44:45], 0
	v_mov_b64_e32 v[46:47], 0
	v_mov_b64_e32 v[56:57], 0
	v_mov_b64_e32 v[58:59], 0
	v_mov_b64_e32 v[60:61], 0
	v_mov_b64_e32 v[62:63], 0
	v_mov_b64_e32 v[64:65], 0
	v_mov_b64_e32 v[66:67], 0
	v_mov_b64_e32 v[68:69], 0
	v_mov_b64_e32 v[70:71], 0
	v_mov_b64_e32 v[80:81], 0
	v_mov_b64_e32 v[82:83], 0
	v_mov_b64_e32 v[84:85], 0
	v_mov_b64_e32 v[86:87], 0
	v_mov_b64_e32 v[96:97], 0
	v_mov_b64_e32 v[98:99], 0
	v_mov_b64_e32 v[100:101], 0
	v_mov_b64_e32 v[102:103], 0
	v_mov_b64_e32 v[112:113], 0
	v_mov_b64_e32 v[114:115], 0
	v_mov_b64_e32 v[116:117], 0
	v_mov_b64_e32 v[118:119], 0
	v_mov_b64_e32 v[72:73], 0
	v_mov_b64_e32 v[74:75], 0
	v_mov_b64_e32 v[76:77], 0
	v_mov_b64_e32 v[78:79], 0
	v_mov_b64_e32 v[88:89], 0
	v_mov_b64_e32 v[90:91], 0
	v_mov_b64_e32 v[92:93], 0
	v_mov_b64_e32 v[94:95], 0
	v_mov_b64_e32 v[104:105], 0
	v_mov_b64_e32 v[106:107], 0
	v_mov_b64_e32 v[108:109], 0
	v_mov_b64_e32 v[110:111], 0
	v_mov_b64_e32 v[120:121], 0
	v_mov_b64_e32 v[122:123], 0
	v_mov_b64_e32 v[124:125], 0
	v_mov_b64_e32 v[126:127], 0

;     __device__ bool next(int i, Unit& u) const { const int L = i * G + c; if (L >= 384) return false; u.pm = L; u.pn = L / 6; return true; }
;     ...
;         const bool has_next = S.next(ui + 1, nxt);
;         const char* nA = has_next ? (const char*)g.A + (size_t)nxt.pm * tsA : cA; const char* nB = has_next ? (const char*)g.Bt + (size_t)nxt.pn * tsB : cB;
;     ...
; #pragma unroll
;         for (int a = 0; a < 2; ++a)
; #pragma unroll
;             for (int b = 0; b < 2; ++b)
; #pragma unroll
;                 for (int m = 0; m < 4; ++m)
; #pragma unroll
;                     for (int n = 0; n < 2; ++n) acc[a][b][m][n] = (f32x4){0.f, 0.f, 0.f, 0.f};
.LBB0_1182:
	s_ashr_i32 s23, s22, 31
	s_lshl_b64 s[24:25], s[22:23], 20
	s_add_u32 s24, s96, s24
	s_addc_u32 s25, s97, s25
	s_ashr_i32 s21, s20, 31
	s_lshl_b64 s[26:27], s[20:21], 20
	s_add_u32 s26, s3, s26
	s_addc_u32 s27, s4, s27
	v_mov_b32_e32 v127, 0
	s_and_b64 vcc, exec, s[0:1]
	v_lshl_add_u32 v208, s28, 8, v220
	s_cbranch_vccnz .LBB0_1193
	s_and_b64 s[28:29], s[6:7], exec
	s_cselect_b32 s21, s25, s35
	s_cselect_b32 s23, s24, s34
	s_cselect_b32 s58, s27, s31
	s_cselect_b32 s59, s26, s30
	s_add_u32 s28, s34, 0x80080
	s_addc_u32 s29, s35, 0
	v_ashrrev_i32_e32 v209, 31, v208
	s_add_u32 s60, s30, 0x100
	v_mov_b32_e32 v0, 0
	v_lshl_add_u64 v[210:211], v[208:209], 2, s[88:89]
	s_addc_u32 s61, s31, 0
	s_mov_b32 s62, 0
	v_mov_b32_e32 v1, 0
	v_mov_b64_e32 v[2:3], 0
	v_mov_b64_e32 v[8:9], 0
	v_mov_b64_e32 v[10:11], 0
	v_mov_b64_e32 v[16:17], 0
	v_mov_b64_e32 v[18:19], 0
	v_mov_b64_e32 v[24:25], 0
	v_mov_b64_e32 v[26:27], 0
	v_mov_b64_e32 v[32:33], 0
	v_mov_b64_e32 v[34:35], 0
	v_mov_b64_e32 v[40:41], 0
	v_mov_b64_e32 v[42:43], 0
	v_mov_b64_e32 v[48:49], 0
	v_mov_b64_e32 v[50:51], 0
	v_mov_b64_e32 v[56:57], 0
	v_mov_b64_e32 v[58:59], 0
	v_mov_b64_e32 v[4:5], 0
	v_mov_b64_e32 v[6:7], 0
	v_mov_b64_e32 v[12:13], 0
	v_mov_b64_e32 v[14:15], 0
	v_mov_b64_e32 v[20:21], 0
	v_mov_b64_e32 v[22:23], 0
	v_mov_b64_e32 v[28:29], 0
	v_mov_b64_e32 v[30:31], 0
	v_mov_b64_e32 v[36:37], 0
	v_mov_b64_e32 v[38:39], 0
	v_mov_b64_e32 v[44:45], 0
	v_mov_b64_e32 v[46:47], 0
	v_mov_b64_e32 v[52:53], 0
	v_mov_b64_e32 v[54:55], 0
	v_mov_b64_e32 v[60:61], 0
	v_mov_b64_e32 v[62:63], 0
	v_mov_b64_e32 v[64:65], 0
	v_mov_b64_e32 v[66:67], 0
	v_mov_b64_e32 v[72:73], 0
	v_mov_b64_e32 v[74:75], 0
	v_mov_b64_e32 v[80:81], 0
	v_mov_b64_e32 v[82:83], 0
	v_mov_b64_e32 v[88:89], 0
	v_mov_b64_e32 v[90:91], 0
	v_mov_b64_e32 v[96:97], 0
	v_mov_b64_e32 v[98:99], 0
	v_mov_b64_e32 v[104:105], 0
	v_mov_b64_e32 v[106:107], 0
	v_mov_b64_e32 v[112:113], 0
	v_mov_b64_e32 v[114:115], 0
	v_mov_b64_e32 v[120:121], 0
	v_mov_b64_e32 v[122:123], 0
	v_mov_b64_e32 v[68:69], 0
	v_mov_b64_e32 v[70:71], 0
	v_mov_b64_e32 v[76:77], 0
	v_mov_b64_e32 v[78:79], 0
	v_mov_b64_e32 v[84:85], 0
	v_mov_b64_e32 v[86:87], 0
	v_mov_b64_e32 v[92:93], 0
	v_mov_b64_e32 v[94:95], 0
	v_mov_b64_e32 v[100:101], 0
	v_mov_b64_e32 v[102:103], 0
	v_mov_b64_e32 v[108:109], 0
	v_mov_b64_e32 v[110:111], 0
	v_mov_b64_e32 v[116:117], 0
	v_mov_b64_e32 v[118:119], 0
	v_mov_b64_e32 v[124:125], 0
	v_mov_b64_e32 v[126:127], 0
	s_branch .LBB0_1185

;     __device__ bool next(int i, Unit& u) const { const int L = i * G + c; if (L >= 384) return false; u.pm = L; u.pn = L / 6; return true; }
;     ...
;         const bool has_next = S.next(ui + 1, nxt);
;         const char* nA = has_next ? (const char*)g.A + (size_t)nxt.pm * tsA : cA; const char* nB = has_next ? (const char*)g.Bt + (size_t)nxt.pn * tsB : cB;
;     ...
; #pragma unroll
;         for (int a = 0; a < 2; ++a)
; #pragma unroll
;             for (int b = 0; b < 2; ++b)
; #pragma unroll
;                 for (int m = 0; m < 4; ++m)
; #pragma unroll
;                     for (int n = 0; n < 2; ++n) acc[a][b][m][n] = (f32x4){0.f, 0.f, 0.f, 0.f};
.LBB0_1265:
	s_ashr_i32 s23, s22, 31
	s_lshl_b64 s[24:25], s[22:23], 20
	s_add_u32 s24, s3, s24
	s_addc_u32 s25, s4, s25
	s_ashr_i32 s21, s20, 31
	s_lshl_b64 s[26:27], s[20:21], 20
	s_add_u32 s26, s5, s26
	v_mov_b32_e32 v127, 0
	s_addc_u32 s27, s40, s27
	s_and_b64 vcc, exec, s[6:7]
	v_mov_b32_e32 v126, 0
	v_mov_b64_e32 v[124:125], 0
	v_mov_b64_e32 v[122:123], 0
	v_mov_b64_e32 v[120:121], 0
	v_mov_b64_e32 v[110:111], 0
	v_mov_b64_e32 v[108:109], 0
	v_mov_b64_e32 v[106:107], 0
	v_mov_b64_e32 v[104:105], 0
	v_mov_b64_e32 v[94:95], 0
	v_mov_b64_e32 v[92:93], 0
	v_mov_b64_e32 v[90:91], 0
	v_mov_b64_e32 v[88:89], 0
	v_mov_b64_e32 v[78:79], 0
	v_mov_b64_e32 v[76:77], 0
	v_mov_b64_e32 v[74:75], 0
	v_mov_b64_e32 v[72:73], 0
	v_mov_b64_e32 v[118:119], 0
	v_mov_b64_e32 v[116:117], 0
	v_mov_b64_e32 v[114:115], 0
	v_mov_b64_e32 v[112:113], 0
	v_mov_b64_e32 v[102:103], 0
	v_mov_b64_e32 v[100:101], 0
	v_mov_b64_e32 v[98:99], 0
	v_mov_b64_e32 v[96:97], 0
	v_mov_b64_e32 v[86:87], 0
	v_mov_b64_e32 v[84:85], 0
	v_mov_b64_e32 v[82:83], 0
	v_mov_b64_e32 v[80:81], 0
	v_mov_b64_e32 v[70:71], 0
	v_mov_b64_e32 v[68:69], 0
	v_mov_b64_e32 v[66:67], 0
	v_mov_b64_e32 v[64:65], 0
	v_mov_b64_e32 v[62:63], 0
	v_mov_b64_e32 v[60:61], 0
	v_mov_b64_e32 v[58:59], 0
	v_mov_b64_e32 v[56:57], 0
	v_mov_b64_e32 v[46:47], 0
	v_mov_b64_e32 v[44:45], 0
	v_mov_b64_e32 v[42:43], 0
	v_mov_b64_e32 v[40:41], 0
	v_mov_b64_e32 v[30:31], 0
	v_mov_b64_e32 v[28:29], 0
	v_mov_b64_e32 v[26:27], 0
	v_mov_b64_e32 v[24:25], 0
	v_mov_b64_e32 v[14:15], 0
	v_mov_b64_e32 v[12:13], 0
	v_mov_b64_e32 v[10:11], 0
	v_mov_b64_e32 v[8:9], 0
	v_mov_b64_e32 v[54:55], 0
	v_mov_b64_e32 v[52:53], 0
	v_mov_b64_e32 v[50:51], 0
	v_mov_b64_e32 v[48:49], 0
	v_mov_b64_e32 v[38:39], 0
	v_mov_b64_e32 v[36:37], 0
	v_mov_b64_e32 v[34:35], 0
	v_mov_b64_e32 v[32:33], 0
	v_mov_b64_e32 v[22:23], 0
	v_mov_b64_e32 v[20:21], 0
	v_mov_b64_e32 v[18:19], 0
	v_mov_b64_e32 v[16:17], 0
	v_mov_b64_e32 v[6:7], 0
	v_mov_b64_e32 v[4:5], 0
	v_mov_b64_e32 v[2:3], 0
	s_waitcnt lgkmcnt(0)
	v_mov_b32_e32 v1, v127
	v_mov_b32_e32 v0, v127
	s_cbranch_vccnz .LBB0_1268
	s_and_b64 s[38:39], s[8:9], exec
	s_cselect_b32 s21, s25, s35
	s_cselect_b32 s23, s24, s34
	s_cselect_b32 s29, s27, s37
	s_cselect_b32 s55, s26, s36
	s_add_u32 s34, s34, 0x80080
	s_addc_u32 s35, s35, 0
	s_add_u32 s56, s36, 0x100
	v_mov_b32_e32 v0, 0
	s_addc_u32 s57, s37, 0
	s_mov_b32 s36, 0
	v_mov_b32_e32 v1, 0
	v_mov_b64_e32 v[2:3], 0
	v_mov_b64_e32 v[4:5], 0
	v_mov_b64_e32 v[6:7], 0
	v_mov_b64_e32 v[16:17], 0
	v_mov_b64_e32 v[18:19], 0
	v_mov_b64_e32 v[20:21], 0
	v_mov_b64_e32 v[22:23], 0
	v_mov_b64_e32 v[32:33], 0
	v_mov_b64_e32 v[34:35], 0
	v_mov_b64_e32 v[36:37], 0
	v_mov_b64_e32 v[38:39], 0
	v_mov_b64_e32 v[48:49], 0
	v_mov_b64_e32 v[50:51], 0
	v_mov_b64_e32 v[52:53], 0
	v_mov_b64_e32 v[54:55], 0
	v_mov_b64_e32 v[8:9], 0
	v_mov_b64_e32 v[10:11], 0
	v_mov_b64_e32 v[12:13], 0
	v_mov_b64_e32 v[14:15], 0
	v_mov_b64_e32 v[24:25], 0
	v_mov_b64_e32 v[26:27], 0
	v_mov_b64_e32 v[28:29], 0
	v_mov_b64_e32 v[30:31], 0
	v_mov_b64_e32 v[40:41], 0
	v_mov_b64_e32 v[42:43], 0
	v_mov_b64_e32 v[44:45], 0
	v_mov_b64_e32 v[46:47], 0
	v_mov_b64_e32 v[56:57], 0
	v_mov_b64_e32 v[58:59], 0
	v_mov_b64_e32 v[60:61], 0
	v_mov_b64_e32 v[62:63], 0
	v_mov_b64_e32 v[64:65], 0
	v_mov_b64_e32 v[66:67], 0
	v_mov_b64_e32 v[68:69], 0
	v_mov_b64_e32 v[70:71], 0
	v_mov_b64_e32 v[80:81], 0
	v_mov_b64_e32 v[82:83], 0
	v_mov_b64_e32 v[84:85], 0
	v_mov_b64_e32 v[86:87], 0
	v_mov_b64_e32 v[96:97], 0
	v_mov_b64_e32 v[98:99], 0
	v_mov_b64_e32 v[100:101], 0
	v_mov_b64_e32 v[102:103], 0
	v_mov_b64_e32 v[112:113], 0
	v_mov_b64_e32 v[114:115], 0
	v_mov_b64_e32 v[116:117], 0
	v_mov_b64_e32 v[118:119], 0
	v_mov_b64_e32 v[72:73], 0
	v_mov_b64_e32 v[74:75], 0
	v_mov_b64_e32 v[76:77], 0
	v_mov_b64_e32 v[78:79], 0
	v_mov_b64_e32 v[88:89], 0
	v_mov_b64_e32 v[90:91], 0
	v_mov_b64_e32 v[92:93], 0
	v_mov_b64_e32 v[94:95], 0
	v_mov_b64_e32 v[104:105], 0
	v_mov_b64_e32 v[106:107], 0
	v_mov_b64_e32 v[108:109], 0
	v_mov_b64_e32 v[110:111], 0
	v_mov_b64_e32 v[120:121], 0
	v_mov_b64_e32 v[122:123], 0
	v_mov_b64_e32 v[124:125], 0
	v_mov_b64_e32 v[126:127], 0

;     __device__ bool next(int i, Unit& u) const { const int L = i * G + c; if (L >= 384) return false; u.pm = L; u.pn = L / 6; return true; }
;     ...
;         const bool has_next = S.next(ui + 1, nxt);
;         const char* nA = has_next ? (const char*)g.A + (size_t)nxt.pm * tsA : cA; const char* nB = has_next ? (const char*)g.Bt + (size_t)nxt.pn * tsB : cB;
;     ...
; #pragma unroll
;         for (int a = 0; a < 2; ++a)
; #pragma unroll
;             for (int b = 0; b < 2; ++b)
; #pragma unroll
;                 for (int m = 0; m < 4; ++m)
; #pragma unroll
;                     for (int n = 0; n < 2; ++n) acc[a][b][m][n] = (f32x4){0.f, 0.f, 0.f, 0.f};
.LBB0_1353:
	s_ashr_i32 s21, s20, 31
	s_lshl_b64 s[22:23], s[20:21], 20
	s_add_u32 s22, s96, s22
	s_addc_u32 s23, s97, s23
	s_ashr_i32 s19, s18, 31
	s_lshl_b64 s[24:25], s[18:19], 20
	s_add_u32 s24, s3, s24
	s_addc_u32 s25, s4, s25
	v_mov_b32_e32 v127, 0
	s_and_b64 vcc, exec, s[0:1]
	v_lshl_add_u32 v208, s26, 8, v220
	s_cbranch_vccnz .LBB0_1364
	s_and_b64 s[26:27], s[6:7], exec
	s_cselect_b32 s19, s23, s31
	s_cselect_b32 s21, s22, s30
	s_cselect_b32 s57, s25, s29
	s_cselect_b32 s58, s24, s28
	s_add_u32 s26, s30, 0x80080
	s_addc_u32 s27, s31, 0
	v_ashrrev_i32_e32 v209, 31, v208
	s_add_u32 s59, s28, 0x100
	v_mov_b32_e32 v0, 0
	v_lshl_add_u64 v[210:211], v[208:209], 2, s[10:11]
	s_addc_u32 s60, s29, 0
	s_mov_b32 s61, 0
	v_mov_b32_e32 v1, 0
	v_mov_b64_e32 v[2:3], 0
	v_mov_b64_e32 v[8:9], 0
	v_mov_b64_e32 v[10:11], 0
	v_mov_b64_e32 v[16:17], 0
	v_mov_b64_e32 v[18:19], 0
	v_mov_b64_e32 v[24:25], 0
	v_mov_b64_e32 v[26:27], 0
	v_mov_b64_e32 v[32:33], 0
	v_mov_b64_e32 v[34:35], 0
	v_mov_b64_e32 v[40:41], 0
	v_mov_b64_e32 v[42:43], 0
	v_mov_b64_e32 v[48:49], 0
	v_mov_b64_e32 v[50:51], 0
	v_mov_b64_e32 v[56:57], 0
	v_mov_b64_e32 v[58:59], 0
	v_mov_b64_e32 v[4:5], 0
	v_mov_b64_e32 v[6:7], 0
	v_mov_b64_e32 v[12:13], 0
	v_mov_b64_e32 v[14:15], 0
	v_mov_b64_e32 v[20:21], 0
	v_mov_b64_e32 v[22:23], 0
	v_mov_b64_e32 v[28:29], 0
	v_mov_b64_e32 v[30:31], 0
	v_mov_b64_e32 v[36:37], 0
	v_mov_b64_e32 v[38:39], 0
	v_mov_b64_e32 v[44:45], 0
	v_mov_b64_e32 v[46:47], 0
	v_mov_b64_e32 v[52:53], 0
	v_mov_b64_e32 v[54:55], 0
	v_mov_b64_e32 v[60:61], 0
	v_mov_b64_e32 v[62:63], 0
	v_mov_b64_e32 v[64:65], 0
	v_mov_b64_e32 v[66:67], 0
	v_mov_b64_e32 v[72:73], 0
	v_mov_b64_e32 v[74:75], 0
	v_mov_b64_e32 v[80:81], 0
	v_mov_b64_e32 v[82:83], 0
	v_mov_b64_e32 v[88:89], 0
	v_mov_b64_e32 v[90:91], 0
	v_mov_b64_e32 v[96:97], 0
	v_mov_b64_e32 v[98:99], 0
	v_mov_b64_e32 v[104:105], 0
	v_mov_b64_e32 v[106:107], 0
	v_mov_b64_e32 v[112:113], 0
	v_mov_b64_e32 v[114:115], 0
	v_mov_b64_e32 v[120:121], 0
	v_mov_b64_e32 v[122:123], 0
	v_mov_b64_e32 v[68:69], 0
	v_mov_b64_e32 v[70:71], 0
	v_mov_b64_e32 v[76:77], 0
	v_mov_b64_e32 v[78:79], 0
	v_mov_b64_e32 v[84:85], 0
	v_mov_b64_e32 v[86:87], 0
	v_mov_b64_e32 v[92:93], 0
	v_mov_b64_e32 v[94:95], 0
	v_mov_b64_e32 v[100:101], 0
	v_mov_b64_e32 v[102:103], 0
	v_mov_b64_e32 v[108:109], 0
	v_mov_b64_e32 v[110:111], 0
	v_mov_b64_e32 v[116:117], 0
	v_mov_b64_e32 v[118:119], 0
	v_mov_b64_e32 v[124:125], 0
	v_mov_b64_e32 v[126:127], 0
	s_branch .LBB0_1356

;     ...
; #pragma unroll
;         for (int a = 0; a < 2; ++a)
; #pragma unroll
;             for (int b = 0; b < 2; ++b)
; #pragma unroll
;                 for (int m = 0; m < 4; ++m)
; #pragma unroll
;                     for (int n = 0; n < 2; ++n) acc[a][b][m][n] = (f32x4){0.f, 0.f, 0.f, 0.f};
.LBB0_1438:
	v_mov_b32_e32 v127, 0
	s_andn2_b64 vcc, exec, s[10:11]
	v_mov_b32_e32 v126, 0
	v_mov_b64_e32 v[146:147], 0
	v_mov_b64_e32 v[144:145], 0
	v_mov_b64_e32 v[124:125], 0
	v_mov_b64_e32 v[118:119], 0
	v_mov_b64_e32 v[116:117], 0
	v_mov_b64_e32 v[110:111], 0
	v_mov_b64_e32 v[108:109], 0
	v_mov_b64_e32 v[102:103], 0
	v_mov_b64_e32 v[100:101], 0
	v_mov_b64_e32 v[94:95], 0
	v_mov_b64_e32 v[92:93], 0
	v_mov_b64_e32 v[86:87], 0
	v_mov_b64_e32 v[84:85], 0
	v_mov_b64_e32 v[78:79], 0
	v_mov_b64_e32 v[76:77], 0
	v_mov_b64_e32 v[154:155], 0
	v_mov_b64_e32 v[152:153], 0
	v_mov_b64_e32 v[150:151], 0
	v_mov_b64_e32 v[148:149], 0
	v_mov_b64_e32 v[122:123], 0
	v_mov_b64_e32 v[120:121], 0
	v_mov_b64_e32 v[114:115], 0
	v_mov_b64_e32 v[112:113], 0
	v_mov_b64_e32 v[106:107], 0
	v_mov_b64_e32 v[104:105], 0
	v_mov_b64_e32 v[98:99], 0
	v_mov_b64_e32 v[96:97], 0
	v_mov_b64_e32 v[90:91], 0
	v_mov_b64_e32 v[88:89], 0
	v_mov_b64_e32 v[82:83], 0
	v_mov_b64_e32 v[80:81], 0
	v_mov_b64_e32 v[66:67], 0
	v_mov_b64_e32 v[64:65], 0
	v_mov_b64_e32 v[62:63], 0
	v_mov_b64_e32 v[60:61], 0
	v_mov_b64_e32 v[54:55], 0
	v_mov_b64_e32 v[52:53], 0
	v_mov_b64_e32 v[46:47], 0
	v_mov_b64_e32 v[44:45], 0
	v_mov_b64_e32 v[30:31], 0
	v_mov_b64_e32 v[28:29], 0
	v_mov_b64_e32 v[22:23], 0
	v_mov_b64_e32 v[20:21], 0
	v_mov_b64_e32 v[14:15], 0
	v_mov_b64_e32 v[12:13], 0
	v_mov_b64_e32 v[10:11], 0
	v_mov_b64_e32 v[8:9], 0
	v_mov_b64_e32 v[74:75], 0
	v_mov_b64_e32 v[72:73], 0
	v_mov_b64_e32 v[70:71], 0
	v_mov_b64_e32 v[68:69], 0
	v_mov_b64_e32 v[58:59], 0
	v_mov_b64_e32 v[56:57], 0
	v_mov_b64_e32 v[50:51], 0
	v_mov_b64_e32 v[48:49], 0
	v_mov_b64_e32 v[38:39], 0
	v_mov_b64_e32 v[36:37], 0
	v_mov_b64_e32 v[34:35], 0
	v_mov_b64_e32 v[32:33], 0
	v_mov_b64_e32 v[6:7], 0
	v_mov_b64_e32 v[4:5], 0
	v_mov_b64_e32 v[2:3], 0
	v_mov_b64_e32 v[0:1], 0
	s_cbranch_vccnz .LBB0_1442
	s_add_u32 s16, s16, 0x160080
	s_addc_u32 s17, s17, 0
	s_add_u32 s44, s18, 0x100
	v_mov_b32_e32 v0, 0
	s_addc_u32 s45, s19, 0
	s_mov_b32 s18, 0
	v_mov_b32_e32 v1, 0
	v_mov_b64_e32 v[2:3], 0
	v_mov_b64_e32 v[4:5], 0
	v_mov_b64_e32 v[6:7], 0
	v_mov_b64_e32 v[8:9], 0
	v_mov_b64_e32 v[10:11], 0
	v_mov_b64_e32 v[12:13], 0
	v_mov_b64_e32 v[14:15], 0
	v_mov_b64_e32 v[20:21], 0
	v_mov_b64_e32 v[22:23], 0
	v_mov_b64_e32 v[28:29], 0
	v_mov_b64_e32 v[30:31], 0
	v_mov_b64_e32 v[36:37], 0
	v_mov_b64_e32 v[38:39], 0
	v_mov_b64_e32 v[44:45], 0
	v_mov_b64_e32 v[46:47], 0
	v_mov_b64_e32 v[16:17], 0
	v_mov_b64_e32 v[18:19], 0
	v_mov_b64_e32 v[24:25], 0
	v_mov_b64_e32 v[26:27], 0
	v_mov_b64_e32 v[32:33], 0
	v_mov_b64_e32 v[34:35], 0
	v_mov_b64_e32 v[40:41], 0
	v_mov_b64_e32 v[42:43], 0
	v_mov_b64_e32 v[48:49], 0
	v_mov_b64_e32 v[50:51], 0
	v_mov_b64_e32 v[52:53], 0
	v_mov_b64_e32 v[54:55], 0
	v_mov_b64_e32 v[56:57], 0
	v_mov_b64_e32 v[58:59], 0
	v_mov_b64_e32 v[60:61], 0
	v_mov_b64_e32 v[62:63], 0
	v_mov_b64_e32 v[64:65], 0
	v_mov_b64_e32 v[66:67], 0
	v_mov_b64_e32 v[68:69], 0
	v_mov_b64_e32 v[70:71], 0
	v_mov_b64_e32 v[72:73], 0
	v_mov_b64_e32 v[74:75], 0
	v_mov_b64_e32 v[76:77], 0
	v_mov_b64_e32 v[78:79], 0
	v_mov_b64_e32 v[84:85], 0
	v_mov_b64_e32 v[86:87], 0
	v_mov_b64_e32 v[92:93], 0
	v_mov_b64_e32 v[94:95], 0
	v_mov_b64_e32 v[100:101], 0
	v_mov_b64_e32 v[102:103], 0
	v_mov_b64_e32 v[108:109], 0
	v_mov_b64_e32 v[110:111], 0
	v_mov_b64_e32 v[80:81], 0
	v_mov_b64_e32 v[82:83], 0
	v_mov_b64_e32 v[88:89], 0
	v_mov_b64_e32 v[90:91], 0
	v_mov_b64_e32 v[96:97], 0
	v_mov_b64_e32 v[98:99], 0
	v_mov_b64_e32 v[104:105], 0
	v_mov_b64_e32 v[106:107], 0
	v_mov_b64_e32 v[112:113], 0
	v_mov_b64_e32 v[114:115], 0
	v_mov_b64_e32 v[116:117], 0
	v_mov_b64_e32 v[118:119], 0
	v_mov_b64_e32 v[120:121], 0
	v_mov_b64_e32 v[122:123], 0
	v_mov_b64_e32 v[124:125], 0
	v_mov_b64_e32 v[126:127], 0
